# grid barrier spin bound raised from 2^16 to the baseline's 2^22 iterations (safety only; no other change vs the L2-prefetch version)
# baseline (speedup 1.0000x reference)
; __device__ __forceinline__ unsigned xb_ld(unsigned* p)              { return __hip_atomic_load(p, __ATOMIC_RELAXED, __HIP_MEMORY_SCOPE_AGENT); }
; #define XB_SPIN(cond, bar) do { unsigned _sp = 0; while (cond) { __builtin_amdgcn_s_sleep(1); \
;     if ((++_sp & 255u) == 0u) { if (xb_ld(&(bar)[XB_TMO])) break; if (_sp > XB_SPIN_CAP) { atomicAdd(&(bar)[XB_TMO], 1u); break; } } } } while (0)
; __device__ __forceinline__ void xcd_barrier(unsigned* bar, volatile LAS unsigned* st) {
;     ...
;         } else {
;             XB_SPIN(xb_ld(&bar[XB_XGEN(x)]) == gen, bar);
;             __builtin_amdgcn_fence(__ATOMIC_ACQUIRE, "agent");
;             asm volatile("s_waitcnt vmcnt(0)" ::: "memory");
.Lxb_spin_0:
	global_load_dword v4, v0, s[8:9] sc1
	s_waitcnt vmcnt(0)
	v_sub_u32_e32 v4, v4, v6
	v_cmp_gt_i32_e32 vcc, 0, v4
	s_cbranch_vccz .Lxb_done_0
	s_sleep 1
	s_add_u32 s0, s0, 1
	s_cmp_lt_u32 s0, 0x400000
	s_cbranch_scc1 .Lxb_spin_0
